# attention tile DMA: each wave copies one contiguous 4KB chunk with one M0 + 4 immediate offsets (on top of mov/canon trims)
# baseline (speedup 1.0000x reference)
; DI int fresh_tid(int wid) { int z = 0; asm volatile("" : "+v"(z)); return wid * 64 + (int)__builtin_amdgcn_mbcnt_hi(~0u, __builtin_amdgcn_mbcnt_lo(~0u, (unsigned)z)); }
; DI void attn_unit(const Params& p, int bh, int qb, char* lds, float lam, int tid, int lane, int wid, const bool build_tab) {
;     const int h = bh & 7, b = bh >> 3;
;     const int map = wid & 1, qblk = wid >> 1, r32 = lane & 31, hi = lane >> 5;
;     const int NT = 2 * qb + 2, ntw = 2 * qb + 1 + (qblk >> 1);
;     float* tab = (float*)(lds + 98304);
;     const char* KGc = p.ws + WS_K + ((size_t)bh * 256 << 14) + tid * 16;
;     const char* VGc = p.ws + WS_V + ((size_t)bh * 256 << 14) + tid * 16;
;     ...
;     const unsigned ldsbase = (unsigned)(uintptr_t)(__attribute__((address_space(3))) char*)lds;
;     ...
;     const int qrow0 = 128 * qb + 32 * qblk;
;     bf16x8 qf[4];
;     { const bf16_t* qrow = (const bf16_t*)(p.ws + WS_Q) + ((size_t)(bh * 2 + map) * SEQ + qrow0 + r32) * 64 + hi * 8;
; #pragma unroll
;       for (int d0 = 0; d0 < 4; ++d0) qf[d0] = *(const bf16x8*)(qrow + 16 * d0); }
;     GLOAD(0, 0);
;     GLOAD(1, 32768);
;     if (build_tab && tid < 320) { const float* rb = p.in[12]; const int rel = tid - 256; tab[tid] = rel < -128 ? 0.f : (rb[t5_bucket_dev(rel) * 8 + h] - rb[15 * 8 + h]) * LOG2E; }
;     asm volatile("s_waitcnt vmcnt(0)" ::: "memory");
;     __syncthreads();
;     const bool grpB = wid >= 4;
;     if (ATT_STAGGER && grpB) __builtin_amdgcn_s_barrier();
;     f32x16 o[4]; o[0] = f32x16{}; o[1] = f32x16{}; o[2] = f32x16{}; o[3] = f32x16{};
;     float l = 0.f, nm = 0.f;
;     f32x16 cinit = f32x16{};
;     int sc = 0, sn1 = 32768, sn2 = 65536;
; __global__ __launch_bounds__(NTHREADS, 2) void hymba_mega(Params p) {
;     ...
;         const int tidA = fresh_tid(wid), laneA = tidA & 63;
;         float lam;
;         { const float a = wave_sum(p.in[7][laneA] * p.in[8][laneA]), c = wave_sum(p.in[9][laneA] * p.in[10][laneA]); lam = __uint_as_float(__builtin_amdgcn_readfirstlane(__float_as_uint(__expf(a) - __expf(c) + 0.2f))); }
.LBB0_343:
	s_cmpk_gt_i32 s2, 0x3ff
	v_mbcnt_lo_u32_b32 v0, -1, v57
	v_mbcnt_hi_u32_b32 v1, -1, v0
	v_and_b32_e32 v0, 63, v1
	v_lshlrev_b32_e32 v2, 2, v0
	global_load_dword v3, v2, s[18:19]
	global_load_dword v4, v2, s[20:21]
	global_load_dword v5, v2, s[22:23]
	global_load_dword v6, v2, s[24:25]
	v_mbcnt_hi_u32_b32 v2, -1, v145
	v_and_b32_e32 v7, 64, v2
	v_xor_b32_e32 v8, 1, v2
	v_add_u32_e32 v7, 64, v7
	v_cmp_lt_i32_e32 vcc, v8, v7
	v_xor_b32_e32 v9, 2, v2
	v_xor_b32_e32 v10, 4, v2
	v_cndmask_b32_e32 v8, v2, v8, vcc
	v_lshlrev_b32_e32 v145, 2, v8
	v_cmp_lt_i32_e32 vcc, v9, v7
	v_xor_b32_e32 v11, 8, v2
	v_xor_b32_e32 v12, 16, v2
	v_cndmask_b32_e32 v9, v2, v9, vcc
	v_lshlrev_b32_e32 v157, 2, v9
	v_cmp_lt_i32_e32 vcc, v10, v7
	v_xor_b32_e32 v13, 32, v2
	s_waitcnt vmcnt(2)
	v_mul_f32_e32 v8, v3, v4
	ds_bpermute_b32 v8, v145, v8
	s_waitcnt vmcnt(0)
	v_mul_f32_e32 v14, v5, v6
	ds_bpermute_b32 v14, v145, v14
	s_waitcnt lgkmcnt(1)
	v_fmac_f32_e32 v8, v3, v4
	ds_bpermute_b32 v3, v157, v8
	s_waitcnt lgkmcnt(1)
	v_fmac_f32_e32 v14, v5, v6
	ds_bpermute_b32 v4, v157, v14
	v_cndmask_b32_e32 v5, v2, v10, vcc
	v_lshlrev_b32_e32 v159, 2, v5
	s_waitcnt lgkmcnt(1)
	v_add_f32_e32 v3, v8, v3
	ds_bpermute_b32 v5, v159, v3
	s_waitcnt lgkmcnt(1)
	v_add_f32_e32 v4, v14, v4
	ds_bpermute_b32 v6, v159, v4
	v_cmp_lt_i32_e32 vcc, v11, v7
	s_waitcnt lgkmcnt(1)
	v_add_f32_e32 v3, v3, v5
	v_cndmask_b32_e32 v8, v2, v11, vcc
	v_lshlrev_b32_e32 v161, 2, v8
	s_waitcnt lgkmcnt(0)
	v_add_f32_e32 v4, v4, v6
	ds_bpermute_b32 v5, v161, v3
	ds_bpermute_b32 v6, v161, v4
	v_cmp_lt_i32_e32 vcc, v12, v7
	s_waitcnt lgkmcnt(1)
	v_add_f32_e32 v3, v3, v5
	v_cndmask_b32_e32 v8, v2, v12, vcc
	v_lshlrev_b32_e32 v163, 2, v8
	s_waitcnt lgkmcnt(0)
	v_add_f32_e32 v4, v4, v6
	ds_bpermute_b32 v5, v163, v3
	ds_bpermute_b32 v6, v163, v4
	v_cmp_lt_i32_e32 vcc, v13, v7
	s_nop 1
	v_cndmask_b32_e32 v2, v2, v13, vcc
	v_lshlrev_b32_e32 v165, 2, v2
	s_waitcnt lgkmcnt(1)
	v_add_f32_e32 v2, v3, v5
	s_waitcnt lgkmcnt(0)
	v_add_f32_e32 v3, v4, v6
	ds_bpermute_b32 v4, v165, v2
	ds_bpermute_b32 v5, v165, v3
	s_waitcnt lgkmcnt(1)
	v_add_f32_e32 v2, v2, v4
	s_waitcnt lgkmcnt(0)
	v_add_f32_e32 v3, v3, v5
	v_mul_f32_e32 v2, 0x3fb8aa3b, v2
	v_mul_f32_e32 v3, 0x3fb8aa3b, v3
	v_exp_f32_e32 v2, v2
	v_exp_f32_e32 v3, v3
	s_nop 0
	v_sub_f32_e32 v2, v2, v3
	s_nop 0
	v_readfirstlane_b32 s4, v2
	s_cbranch_scc1 .LBB0_386
	v_lshrrev_b32_e32 v7, 5, v0
	v_mov_b32_e32 v2, 0x3e4ccccd
	v_mov_b32_e32 v147, 0
	v_lshlrev_b32_e32 v146, 4, v7
	v_add_f32_e32 v167, s4, v2
	v_lshl_add_u64 v[4:5], s[42:43], 0, v[146:147]
	s_mov_b64 s[4:5], 0x1a400000
	v_lshl_add_u64 v[148:149], v[4:5], 0, s[4:5]
	v_lshlrev_b32_e32 v4, 1, v0
	s_lshr_b32 s6, s41, 7
	v_and_b32_e32 v171, 32, v4
	v_lshlrev_b32_e32 v4, 3, v0
	s_lshl_b32 s59, s6, 5
	v_and_b32_e32 v202, 24, v4
	v_lshlrev_b32_e32 v4, 4, v1
	s_lshl_b32 s6, s6, 14
	v_and_b32_e32 v4, 0xc0, v4
	s_add_i32 s6, s6, 0
	v_add_u32_e32 v6, s33, v1
	v_and_b32_e32 v144, 31, v1
	v_lshl_or_b32 v203, v7, 8, v4
	v_mov_b32_e32 v4, s6
	s_movk_i32 s14, 0x110
	v_and_b32_e32 v1, 15, v1
	v_mad_u32_u24 v10, v144, s14, v4
	v_lshlrev_b32_e32 v4, 5, v1
	v_mov_b32_e32 v5, v147
	v_lshl_add_u32 v206, v0, 2, s6
	v_lshl_add_u32 v207, v1, 4, s6
	v_lshlrev_b32_e32 v208, 3, v1
	v_lshl_add_u64 v[154:155], s[26:27], 0, v[4:5]
	s_movk_i32 s6, 0x100
	v_add_u32_e32 v1, 0xffffff00, v6
	v_sub_u32_e32 v4, 0x100, v6
	v_cmp_lt_u32_e32 vcc, s6, v6
	v_max_i32_e32 v1, v1, v4
	s_movk_i32 s6, 0x5b
	v_lshrrev_b32_e32 v156, 4, v0
	v_cndmask_b32_e64 v0, 0, 16, vcc
	v_cmp_gt_u32_e32 vcc, s6, v1
	s_bfe_u32 s58, s41, 0x10006
	v_min_u32_e32 v5, 8, v1
	v_cndmask_b32_e64 v4, 15, 14, vcc
	v_cmp_lt_u32_e32 vcc, 63, v1
	s_lshl_b32 s60, s53, 10
	s_lshl_b32 s61, s58, 13
	v_cndmask_b32_e32 v4, 13, v4, vcc
	v_cmp_lt_u32_e32 vcc, 45, v1
	v_lshlrev_b32_e32 v2, 4, v6
	s_add_i32 s7, 0, 0x18000
	v_cndmask_b32_e32 v4, 12, v4, vcc
	v_cmp_lt_u32_e32 vcc, 31, v1
	s_add_i32 s60, s60, 0
	s_add_i32 s10, s61, 0
	v_cndmask_b32_e32 v4, 11, v4, vcc
	v_cmp_gt_u32_e32 vcc, 12, v1
	s_and_b32 s12, 64, s41
	v_ashrrev_i32_e32 v3, 31, v2
	v_cndmask_b32_e32 v5, 9, v5, vcc
	v_cmp_lt_u32_e32 vcc, 22, v1
	v_lshlrev_b32_e32 v204, 10, v7
	s_cmp_eq_u32 s58, 0
	v_cndmask_b32_e32 v4, 10, v4, vcc
	v_cmp_gt_u32_e32 vcc, 16, v1
	v_lshl_add_u64 v[2:3], s[42:43], 0, v[2:3]
	s_mov_b64 s[4:5], 0x1e400000
	v_cndmask_b32_e32 v1, v4, v5, vcc
	v_add_u32_e32 v9, s10, v204
	s_cselect_b64 s[10:11], -1, 0
	s_cmp_lg_u32 s12, 0
	v_or_b32_e32 v0, v1, v0
	v_lshl_add_u64 v[150:151], v[2:3], 0, s[4:5]
	s_mov_b64 s[4:5], 0x22400000
	v_lshl_add_u32 v169, v6, 2, s7
	s_cselect_b64 s[12:13], -1, 0
	s_add_u32 s14, s42, 0x16400000
	v_lshlrev_b32_e32 v210, 3, v0
	v_add_u32_e32 v211, s7, v146
	s_mov_b64 s[6:7], 0x1e40c000
	v_lshlrev_b32_e32 v0, 2, v144
	v_lshl_add_u64 v[152:153], v[2:3], 0, s[4:5]
	s_movk_i32 s4, 0x140
	s_addc_u32 s15, s43, 0
	v_lshl_add_u64 v[172:173], v[2:3], 0, s[6:7]
	v_sub_u32_e32 v0, v146, v0
	s_and_b32 s6, s41, 0xffffff80
	v_lshlrev_b32_e32 v8, 3, v7
	v_cmp_gt_i32_e64 s[8:9], s4, v6
	s_movk_i32 s4, 0x7f
	v_lshlrev_b32_e32 v205, 4, v144
	v_add3_u32 v7, 0, v171, v202
	v_subrev_u32_e32 v0, s6, v0
	v_cmp_lt_i32_e64 s[4:5], s4, v6
	v_mul_u32_u24_e32 v209, 0x110, v156
	v_or_b32_e32 v158, 4, v156
	v_or_b32_e32 v160, 8, v156
	v_or_b32_e32 v162, 12, v156
	v_or_b32_e32 v164, 16, v156
	v_or_b32_e32 v166, 20, v156
	v_or_b32_e32 v168, 24, v156
	v_or_b32_e32 v170, 28, v156
	s_lshl_b32 s62, s2, 1
	s_lshl_b32 s63, s3, 1
	v_add_u32_e32 v212, 0, v0
	v_add_u32_e32 v213, 0, v146
	v_or_b32_e32 v214, s59, v144
	s_mov_b64 s[16:17], 0x2000
	s_mov_b64 s[18:19], 0x4000
	s_mov_b64 s[20:21], 0x6000
	s_mov_b64 s[22:23], 0x8000
	s_mov_b64 s[24:25], 0xa000
	s_mov_b32 s41, 0x41000000
	s_mov_b64 s[26:27], 0x4000000
	s_mov_b64 s[30:31], 0x4002000
	v_mov_b32_e32 v215, 0x358637bd
	s_mov_b32 s64, 0x26400000
	v_add_u32_e32 v216, v9, v205
	v_add_u32_e32 v217, v7, v203
	v_add_u32_e32 v218, v10, v8
	s_mov_b32 s65, s2
	s_mul_i32 s94, s60, 3
	s_cmp_lt_u32 s59, 64
	s_cbranch_scc1 .Lccd_lo
	s_add_u32 s94, s94, 0x3ffc000
.Lccd_lo:
	s_mov_b32 s95, 0
	s_lshl_b32 s93, s60, 2
	s_branch .LBB0_346

; DI void attn_unit(const Params& p, int bh, int qb, char* lds, float lam, int tid, int lane, int wid, const bool build_tab) {
;     ...
;             const lds_cptr kp = (lds_cptr)lds + sc + map * 8192 + hi * 1024 + r32 * 16;
;             bf16x8 kf[8];
; #pragma unroll
;             for (int d0 = 0; d0 < 4; ++d0) {
;                 kf[2 * d0] = *(const __attribute__((address_space(3))) bf16x8*)(kp + d0 * 2048);
;                 kf[2 * d0 + 1] = *(const __attribute__((address_space(3))) bf16x8*)(kp + d0 * 2048 + 512);
;             }
;             f32x16 s0 = cinit, s1 = cinit;
; #pragma unroll
;             for (int d0 = 0; d0 < 4; ++d0) { s0 = MFMA32(kf[2 * d0], qf[d0], s0); s1 = MFMA32(kf[2 * d0 + 1], qf[d0], s1); }
;             LOADV(va, 0);
;             if (t >= 2 * qb - 2) {
;                 const float* tb = tab + (64 * t - (qrow0 + r32) + 256 + 4 * hi);
; #pragma unroll
;                 for (int i = 0; i < 16; ++i) {
;                     s0[i] += tb[(i & 3) + 8 * (i >> 2)];
;                     s1[i] += tb[(i & 3) + 8 * (i >> 2) + 32];
;                 }
;             }
;             float mxa = MX3(s0[0], s0[1], s1[0]), mxb = MX3(s0[2], s0[3], s1[1]); mxa = MX3(mxa, s1[2], s1[3]);
; #pragma unroll
;             for (int r = 4; r < 16; r += 4) { mxa = MX3(mxa, s0[r], s0[r + 1]); mxb = MX3(mxb, s0[r + 2], s0[r + 3]); mxa = MX3(mxa, s1[r], s1[r + 1]); mxb = MX3(mxb, s1[r + 2], s1[r + 3]); }
;             float mx = swap_max(__builtin_fmaxf(mxa, mxb));
;             const bool first = (t == 0);
;             if (first || __builtin_amdgcn_ballot_w64(mx > 8.0f) != 0ull) {
;                 const float dl = first ? mx : __builtin_fmaxf(mx, 0.f);
;                 const float f = first ? 1.0f : ex2(-dl);
;                 l *= f; nm -= dl;
; #pragma unroll
;                 for (int i = 0; i < 16; ++i) { o[0][i] *= f; o[1][i] *= f; o[2][i] *= f; o[3][i] *= f; cinit[i] = nm; s0[i] -= dl; s1[i] -= dl; }
;             }
;             asm volatile("s_waitcnt vmcnt(0)" ::: "memory");
;             if (t + 2 < NT) GLOAD(t + 2, sn2);
;             float rs0 = 0.f, rs1 = 0.f;
;     ...
;             EXPQ(s0, 0, rs0, pf[0]);
;             LOADV(vb, 1);
;             MF4(va, pf[0]);
;             EXPQ(s0, 8, rs1, pf[1]);
;             LOADV(va, 2);
;             MF4(vb, pf[1]);
;             EXPQ(s1, 0, rs0, pf[2]);
;             LOADV(vb, 3);
;             MF4(va, pf[2]);
.LBB0_350:
	s_or_b64 exec, exec, s[54:55]
	s_waitcnt vmcnt(0)
	s_waitcnt lgkmcnt(0)
	s_barrier
	ds_read_b128 v[0:3], v216
	ds_read_b128 v[16:19], v216 offset:512
	s_waitcnt vmcnt(3) lgkmcnt(1)
	v_mfma_f32_32x32x16_bf16 v[0:15], v[0:3], v[112:115], 0
	v_lshl_add_u64 v[178:179], v[184:185], 0, s[22:23]
	s_add_i32 s55, s60, 0x10000
	v_lshl_add_u64 v[180:181], v[184:185], 0, s[24:25]
	s_add_i32 s56, s60, 0x12000
	v_lshl_add_u64 v[176:177], v[182:183], 0, s[22:23]
	s_add_i32 s57, s60, 0x14000
	v_lshl_add_u64 v[190:191], v[182:183], 0, s[24:25]
	s_waitcnt lgkmcnt(0)
	v_mfma_f32_32x32x16_bf16 v[64:79], v[16:19], v[112:115], 0
	ds_read_b128 v[16:19], v216 offset:2048
	ds_read_b128 v[20:23], v216 offset:2560
	s_add_i32 s70, s60, 0x16000
	s_lshl_b32 s77, s81, 1
	s_add_i32 s78, s35, s77
	s_lshr_b32 s54, s65, 3
	s_add_i32 s78, s78, 1
	s_add_i32 s79, s77, -2
	s_waitcnt vmcnt(2) lgkmcnt(1)
	v_mfma_f32_32x32x16_bf16 v[0:15], v[16:19], v[116:119], v[0:15]
	s_mov_b32 s80, 0x10000
	s_waitcnt lgkmcnt(0)
	v_mfma_f32_32x32x16_bf16 v[64:79], v[20:23], v[116:119], v[64:79]
	ds_read_b128 v[16:19], v216 offset:4096
	ds_read_b128 v[20:23], v216 offset:4608
	s_waitcnt vmcnt(1) lgkmcnt(1)
	v_mfma_f32_32x32x16_bf16 v[0:15], v[16:19], v[120:123], v[0:15]
	s_waitcnt lgkmcnt(0)
	v_mfma_f32_32x32x16_bf16 v[64:79], v[20:23], v[120:123], v[64:79]
	ds_read_b128 v[16:19], v216 offset:6144
	ds_read_b128 v[20:23], v216 offset:6656
	ds_read_b64_tr_b16 v[24:25], v217 offset:16384
	ds_read_b64_tr_b16 v[26:27], v217 offset:16896
	ds_read_b64_tr_b16 v[28:29], v217 offset:20480
	ds_read_b64_tr_b16 v[30:31], v217 offset:20992
	s_waitcnt vmcnt(0) lgkmcnt(5)
	v_mfma_f32_32x32x16_bf16 v[0:15], v[16:19], v[124:127], v[0:15]
	ds_read_b64_tr_b16 v[16:17], v217 offset:24576
	ds_read_b64_tr_b16 v[18:19], v217 offset:25088
	ds_read_b64_tr_b16 v[96:97], v217 offset:28672
	ds_read_b64_tr_b16 v[98:99], v217 offset:29184
	s_waitcnt vmcnt(0)
	s_mov_b32 s7, m0
	s_mov_b32 m0, s55
	s_nop 0
	global_load_lds_dwordx4 v[178:179], off
	s_mov_b32 m0, s7
	s_nop 7
	v_max_f32_e32 v32, v1, v1
	s_waitcnt lgkmcnt(8)
	v_mfma_f32_32x32x16_bf16 v[64:79], v[20:23], v[124:127], v[64:79]
	v_max_f32_e32 v33, v0, v0
	v_max_f32_e32 v32, v33, v32
	s_mov_b32 s7, m0
	s_mov_b32 m0, s56
	s_nop 0
	global_load_lds_dwordx4 v[180:181], off
	s_mov_b32 m0, s7
	s_nop 0
	s_mov_b32 s7, m0
	s_mov_b32 m0, s57
	s_nop 0
	global_load_lds_dwordx4 v[176:177], off
	s_mov_b32 m0, s7
	s_nop 8
	v_max3_f32 v20, v2, v3, v65
	v_max3_f32 v21, v32, v64, v66
	v_max3_f32 v21, v21, v67, v4
	v_max3_f32 v20, v20, v6, v7
	v_max3_f32 v21, v21, v5, v68
	v_max3_f32 v20, v20, v70, v71
	v_max3_f32 v21, v21, v69, v8
	v_max3_f32 v20, v20, v10, v11
	v_max3_f32 v21, v21, v9, v72
	v_max3_f32 v20, v20, v74, v75
	v_max3_f32 v21, v21, v73, v12
	v_max3_f32 v20, v20, v14, v15
	v_max3_f32 v21, v21, v13, v76
	v_max3_f32 v20, v20, v78, v79
	v_max3_f32 v20, v21, v77, v20
	v_mov_b32_e32 v21, v20
	s_nop 1
	v_permlane32_swap_b32_e32 v20, v21
	v_max_f32_e32 v21, v21, v21
	v_max_f32_e32 v20, v20, v20
	v_max_f32_e32 v146, v20, v21
	v_sub_f32_e32 v0, v0, v146
	v_sub_f32_e32 v1, v1, v146
	v_sub_f32_e32 v2, v2, v146
	v_sub_f32_e32 v3, v3, v146
	v_sub_f32_e32 v4, v4, v146
	v_sub_f32_e32 v5, v5, v146
	v_sub_f32_e32 v6, v6, v146
	v_sub_f32_e32 v7, v7, v146
	v_exp_f32_e32 v94, v0
	v_exp_f32_e32 v92, v1
	v_exp_f32_e32 v90, v2
	v_exp_f32_e32 v88, v3
	v_exp_f32_e32 v86, v4
	v_exp_f32_e32 v84, v5
	v_exp_f32_e32 v82, v6
	v_exp_f32_e32 v80, v7
	v_cvt_pk_bf16_f32 v0, v94, v92
	v_cvt_pk_bf16_f32 v1, v90, v88
	v_cvt_pk_bf16_f32 v2, v86, v84
	v_cvt_pk_bf16_f32 v3, v82, v80
	v_sub_f32_e32 v81, v8, v146
	v_sub_f32_e32 v83, v9, v146
	s_waitcnt lgkmcnt(6)
	v_mfma_f32_32x32x16_bf16 v[48:63], v[24:27], v[0:3], 0
	v_sub_f32_e32 v85, v10, v146
	v_sub_f32_e32 v87, v11, v146
	v_sub_f32_e32 v104, v12, v146
	v_sub_f32_e32 v105, v13, v146
	v_sub_f32_e32 v106, v14, v146
	v_sub_f32_e32 v107, v15, v146
	s_mov_b32 s7, m0
	s_mov_b32 m0, s70
	s_nop 0
	global_load_lds_dwordx4 v[190:191], off
	s_mov_b32 m0, s7
	ds_read_b64_tr_b16 v[100:101], v217 offset:17408
	ds_read_b64_tr_b16 v[102:103], v217 offset:17920
	v_exp_f32_e32 v95, v81
	v_exp_f32_e32 v93, v83
	v_exp_f32_e32 v91, v85
	v_exp_f32_e32 v89, v87
	v_exp_f32_e32 v87, v104
	v_exp_f32_e32 v85, v105
	v_exp_f32_e32 v83, v106
	v_exp_f32_e32 v81, v107
	s_waitcnt lgkmcnt(6)
	v_mfma_f32_32x32x16_bf16 v[32:47], v[28:31], v[0:3], 0
	ds_read_b64_tr_b16 v[104:105], v217 offset:18432
	ds_read_b64_tr_b16 v[106:107], v217 offset:18944
	v_sub_f32_e32 v64, v64, v146
	v_sub_f32_e32 v65, v65, v146
	v_sub_f32_e32 v68, v68, v146
	v_sub_f32_e32 v69, v69, v146
	v_sub_f32_e32 v70, v70, v146
	v_sub_f32_e32 v71, v71, v146
	s_waitcnt lgkmcnt(6)
	v_mfma_f32_32x32x16_bf16 v[16:31], v[16:19], v[0:3], 0
	v_exp_f32_e32 v110, v64
	v_exp_f32_e32 v138, v68
	v_exp_f32_e32 v140, v69
	v_exp_f32_e32 v142, v70
	v_exp_f32_e32 v174, v71
	v_sub_f32_e32 v64, v72, v146
	v_cvt_pk_bf16_f32 v70, v138, v140
	s_waitcnt lgkmcnt(4)
; #define GLOAD(t_, slotoff_) do { const char* kb_ = KGc + ((size_t)(t_) << 14); const char* vb_ = VGc + ((size_t)(t_) << 14); \
;         const unsigned d_ = (unsigned)__builtin_amdgcn_readfirstlane((int)(ldsbase + (slotoff_) + wid * 1024)); \
;         GLDS16(kb_, d_); GLDS16(kb_ + 8192, d_ + 8192u); GLDS16(vb_, d_ + 16384u); GLDS16(vb_ + 8192, d_ + 24576u); } while (0)
; #define SCHEDB() __builtin_amdgcn_sched_barrier(0)
; #define LOADV(dst, ks_) do { _Pragma("unroll") for (int dvb = 0; dvb < 4; ++dvb) { dst[2 * dvb] = vtr(vp + dvb * 4096 + (ks_) * 1024); dst[2 * dvb + 1] = vtr(vp + dvb * 4096 + (ks_) * 1024 + 512); } } while (0)
; #define MF4(src, pfrag) do { _Pragma("unroll") for (int dvb = 0; dvb < 4; ++dvb) { \
;         const bf16x8 vf_ = __builtin_shufflevector(src[2 * dvb], src[2 * dvb + 1], 0, 1, 2, 3, 4, 5, 6, 7); o[dvb] = MFMA32(vf_, pfrag, o[dvb]); } } while (0)
; #define EXPQ(S, lo_, RS, PF) do { _Pragma("unroll") for (int i = lo_; i < lo_ + 8; ++i) { S[i] = ex2(S[i]); RS += S[i]; } \
;               u32x4 w_; w_.x = pk2(S[lo_], S[lo_ + 1]); w_.y = pk2(S[lo_ + 2], S[lo_ + 3]); w_.z = pk2(S[lo_ + 4], S[lo_ + 5]); w_.w = pk2(S[lo_ + 6], S[lo_ + 7]); PF = __builtin_bit_cast(bf16x8, w_); } while (0)
; DI void attn_unit(const Params& p, int bh, int qb, char* lds, float lam, int tid, int lane, int wid, const bool build_tab) {
;     ...
;             EXPQ(s0, 0, rs0, pf[0]);
;             LOADV(vb, 1);
;             MF4(va, pf[0]);
;             EXPQ(s0, 8, rs1, pf[1]);
;             LOADV(va, 2);
;             MF4(vb, pf[1]);
;             EXPQ(s1, 0, rs0, pf[2]);
;             LOADV(vb, 3);
;             MF4(va, pf[2]);
;             EXPQ(s1, 8, rs1, pf[3]);
;             MF4(vb, pf[3]);
;             l += rs0 + rs1;
;     ...
;         } else {
;             asm volatile("s_waitcnt vmcnt(0)" ::: "memory");
;             if (t + 2 < NT) GLOAD(t + 2, sn2);
;         }
;         SCHEDB();
;         __builtin_amdgcn_s_barrier();
;         SCHEDB();
;         { const int tmp = sc; sc = sn1; sn1 = sn2; sn2 = tmp; }
	v_mfma_f32_32x32x16_bf16 v[0:15], v[96:99], v[0:3], 0
	v_cvt_pk_bf16_f32 v96, v95, v93
	v_cvt_pk_bf16_f32 v97, v91, v89
	v_cvt_pk_bf16_f32 v98, v87, v85
	v_cvt_pk_bf16_f32 v99, v83, v81
	v_cvt_pk_bf16_f32 v71, v142, v174
	v_exp_f32_e32 v111, v64
	v_sub_f32_e32 v76, v76, v146
	s_waitcnt lgkmcnt(2)
	v_mfma_f32_32x32x16_bf16 v[48:63], v[100:103], v[96:99], v[48:63]
	ds_read_b64_tr_b16 v[100:101], v217 offset:21504
	ds_read_b64_tr_b16 v[102:103], v217 offset:22016
	ds_read_b64_tr_b16 v[108:109], v217 offset:19968
	v_sub_f32_e32 v77, v77, v146
	v_sub_f32_e32 v78, v78, v146
	v_sub_f32_e32 v79, v79, v146
	v_exp_f32_e32 v139, v76
	v_exp_f32_e32 v141, v77
	v_exp_f32_e32 v143, v78
	s_waitcnt lgkmcnt(1)
	v_mfma_f32_32x32x16_bf16 v[32:47], v[100:103], v[96:99], v[32:47]
	ds_read_b64_tr_b16 v[100:101], v217 offset:25600
	ds_read_b64_tr_b16 v[102:103], v217 offset:26112
	ds_read_b64_tr_b16 v[128:129], v217 offset:29696
	ds_read_b64_tr_b16 v[130:131], v217 offset:30208
	ds_read_b64_tr_b16 v[132:133], v217 offset:26624
	ds_read_b64_tr_b16 v[134:135], v217 offset:27136
	v_exp_f32_e32 v175, v79
	s_lshl_b32 s7, s62, 22
	s_and_b32 s82, s7, 0x3800000
	s_mov_b32 s7, 1
	s_waitcnt lgkmcnt(4)
	v_mfma_f32_32x32x16_bf16 v[16:31], v[100:103], v[96:99], v[16:31]
	v_sub_f32_e32 v100, v66, v146
	v_sub_f32_e32 v101, v67, v146
	v_exp_f32_e32 v136, v101
	ds_read_b64_tr_b16 v[66:67], v217 offset:28160
	s_waitcnt lgkmcnt(3)
	v_mfma_f32_32x32x16_bf16 v[0:15], v[128:131], v[96:99], v[0:15]
	v_exp_f32_e32 v128, v65
	v_exp_f32_e32 v130, v100
	ds_read_b64_tr_b16 v[96:97], v217 offset:22528
	ds_read_b64_tr_b16 v[98:99], v217 offset:23040
	ds_read_b64_tr_b16 v[100:101], v217 offset:23552
	ds_read_b64_tr_b16 v[102:103], v217 offset:24064
	v_sub_f32_e32 v65, v73, v146
	v_cvt_pk_bf16_f32 v68, v110, v128
	v_cvt_pk_bf16_f32 v69, v130, v136
	v_exp_f32_e32 v129, v65
	s_nop 0
	v_mfma_f32_32x32x16_bf16 v[48:63], v[104:107], v[68:71], v[48:63]
	ds_read_b64_tr_b16 v[106:107], v217 offset:19456
	v_sub_f32_e32 v104, v74, v146
	v_sub_f32_e32 v105, v75, v146
	v_exp_f32_e32 v131, v104
	v_exp_f32_e32 v137, v105
	s_waitcnt lgkmcnt(3)
	v_mfma_f32_32x32x16_bf16 v[32:47], v[96:99], v[68:71], v[32:47]
	ds_read_b64_tr_b16 v[96:97], v217 offset:30720
	ds_read_b64_tr_b16 v[98:99], v217 offset:31232
	ds_read_b64_tr_b16 v[72:73], v217 offset:31744
	ds_read_b64_tr_b16 v[74:75], v217 offset:32256
	ds_read_b64_tr_b16 v[64:65], v217 offset:27648
	v_mfma_f32_32x32x16_bf16 v[16:31], v[132:135], v[68:71], v[16:31]
	s_waitcnt lgkmcnt(3)
	v_mfma_f32_32x32x16_bf16 v[0:15], v[96:99], v[68:71], v[0:15]
	v_cvt_pk_bf16_f32 v68, v111, v129
	v_cvt_pk_bf16_f32 v69, v131, v137
	v_cvt_pk_bf16_f32 v70, v139, v141
	v_cvt_pk_bf16_f32 v71, v143, v175
	s_waitcnt lgkmcnt(0)
	s_nop 0
	v_mfma_f32_32x32x16_bf16 v[16:31], v[64:67], v[68:71], v[16:31]
	v_add_f32_e64 v66, v94, 0
	v_add_f32_e64 v67, v95, 0
	v_sub_f32_e32 v64, 0, v146
	v_add_f32_e64 v66, v92, v66
	v_add_f32_e64 v67, v93, v67
	v_pk_add_f32 v[66:67], v[90:91], v[66:67]
	s_nop 0
	v_pk_add_f32 v[66:67], v[88:89], v[66:67]
	v_mfma_f32_32x32x16_bf16 v[48:63], v[106:109], v[68:71], v[48:63]
	v_add_f32_e64 v66, v86, v66
	v_add_f32_e64 v67, v87, v67
	v_add_f32_e64 v66, v84, v66
	v_add_f32_e64 v67, v85, v67
	v_add_f32_e64 v66, v82, v66
	v_add_f32_e64 v67, v83, v67
	v_pk_add_f32 v[66:67], v[80:81], v[66:67]
	v_mfma_f32_32x32x16_bf16 v[32:47], v[100:103], v[68:71], v[32:47]
	v_add_f32_e64 v66, v110, v66
	v_add_f32_e64 v67, v111, v67
	v_add_f32_e64 v66, v128, v66
	v_add_f32_e64 v67, v129, v67
	v_add_f32_e64 v66, v130, v66
	v_add_f32_e64 v67, v131, v67
	v_pk_add_f32 v[66:67], v[136:137], v[66:67]
	v_mfma_f32_32x32x16_bf16 v[0:15], v[72:75], v[68:71], v[0:15]
	v_add_f32_e64 v66, v138, v66
	v_add_f32_e64 v67, v139, v67
	v_add_f32_e64 v66, v140, v66
	v_add_f32_e64 v67, v141, v67
	v_add_f32_e64 v66, v142, v66
	v_add_f32_e64 v67, v143, v67
	v_pk_add_f32 v[66:67], v[174:175], v[66:67]
	s_nop 0
	v_add_f32_e32 v65, v66, v67
	v_add_f32_e32 v146, 0, v65
	s_barrier
	s_ashr_i32 s51, s50, 31
	s_lshl_b64 s[50:51], s[50:51], 22
	s_add_u32 s50, s82, s50
	s_addc_u32 s51, 0, s51
	v_lshl_add_u64 v[174:175], v[172:173], 0, s[50:51]
	v_lshl_add_u64 v[174:175], v[174:175], 0, s[94:95]
	s_lshl_b32 s81, s81, 9
	v_subrev_u32_e32 v219, s81, v212
	s_mov_b32 s82, 0
	s_mov_b32 s50, 0x8000
	s_movk_i32 s83, 0xff00
	v_mov_b64_e32 v[200:201], v[174:175]
	v_mov_b32_e32 v65, v64
	v_mov_b32_e32 v66, v64
	v_mov_b32_e32 v67, v64
	v_mov_b32_e32 v68, v64
	v_mov_b32_e32 v69, v64
	v_mov_b32_e32 v70, v64
	v_mov_b32_e32 v71, v64
	v_mov_b32_e32 v72, v64
	v_mov_b32_e32 v73, v64
	v_mov_b32_e32 v74, v64
	v_mov_b32_e32 v75, v64
	v_mov_b32_e32 v76, v64
	v_mov_b32_e32 v77, v64
	v_mov_b32_e32 v78, v64
	v_mov_b32_e32 v79, v64
	s_mov_b32 s84, s50
	s_cmp_ge_u32 s7, s78
	s_mov_b64 s[50:51], -1
	s_cbranch_scc0 .LBB0_352

; #define GLOAD(t_, slotoff_) do { const char* kb_ = KGc + ((size_t)(t_) << 14); const char* vb_ = VGc + ((size_t)(t_) << 14); \
;         const unsigned d_ = (unsigned)__builtin_amdgcn_readfirstlane((int)(ldsbase + (slotoff_) + wid * 1024)); \
;         GLDS16(kb_, d_); GLDS16(kb_ + 8192, d_ + 8192u); GLDS16(vb_, d_ + 16384u); GLDS16(vb_ + 8192, d_ + 24576u); } while (0)
; DI void attn_unit(const Params& p, int bh, int qb, char* lds, float lam, int tid, int lane, int wid, const bool build_tab) {
;     ...
;             asm volatile("s_waitcnt vmcnt(0)" ::: "memory");
;             if (t + 2 < NT) GLOAD(t + 2, sn2);
.LBB0_357:
	s_waitcnt vmcnt(0)
	s_cmp_ge_u32 s7, s77
	s_cbranch_scc1 .LBB0_359
	s_add_i32 s92, s82, s93
	s_mov_b32 m0, s92
	s_nop 0
	global_load_lds_dwordx4 v[200:201], off
	global_load_lds_dwordx4 v[200:201], off offset:1024
	global_load_lds_dwordx4 v[200:201], off offset:2048
	global_load_lds_dwordx4 v[200:201], off offset:3072

; #define GLOAD(t_, slotoff_) do { const char* kb_ = KGc + ((size_t)(t_) << 14); const char* vb_ = VGc + ((size_t)(t_) << 14); \
;         const unsigned d_ = (unsigned)__builtin_amdgcn_readfirstlane((int)(ldsbase + (slotoff_) + wid * 1024)); \
;         GLDS16(kb_, d_); GLDS16(kb_ + 8192, d_ + 8192u); GLDS16(vb_, d_ + 16384u); GLDS16(vb_ + 8192, d_ + 24576u); } while (0)
; DI void attn_unit(const Params& p, int bh, int qb, char* lds, float lam, int tid, int lane, int wid, const bool build_tab) {
;     ...
;             asm volatile("s_waitcnt vmcnt(0)" ::: "memory");
;             if (t + 2 < NT) GLOAD(t + 2, sn2);
.LBB0_377:
	s_waitcnt vmcnt(0)
	s_cmp_ge_u32 s51, s55
	s_cbranch_scc1 .LBB0_379
	s_add_i32 s92, s67, s93
	s_mov_b32 m0, s92
	s_nop 0
	global_load_lds_dwordx4 v[174:175], off
	global_load_lds_dwordx4 v[174:175], off offset:1024
	global_load_lds_dwordx4 v[174:175], off offset:2048
	global_load_lds_dwordx4 v[174:175], off offset:3072

; __global__ __launch_bounds__(NTHREADS, 2) void hymba_mega(Params p) {
	.amdhsa_kernel _Z10hymba_mega6Params
		.amdhsa_group_segment_fixed_size 0
		.amdhsa_private_segment_fixed_size 0
		.amdhsa_kernarg_size 392
		.amdhsa_user_sgpr_count 2
		.amdhsa_user_sgpr_dispatch_ptr 0
		.amdhsa_user_sgpr_queue_ptr 0
		.amdhsa_user_sgpr_kernarg_segment_ptr 1
		.amdhsa_user_sgpr_dispatch_id 0
		.amdhsa_user_sgpr_kernarg_preload_length 0
		.amdhsa_user_sgpr_kernarg_preload_offset 0
		.amdhsa_user_sgpr_private_segment_size 0
		.amdhsa_uses_dynamic_stack 0
		.amdhsa_enable_private_segment 0
		.amdhsa_system_sgpr_workgroup_id_x 1
		.amdhsa_system_sgpr_workgroup_id_y 0
		.amdhsa_system_sgpr_workgroup_id_z 0
		.amdhsa_system_sgpr_workgroup_info 0
		.amdhsa_system_vgpr_workitem_id 2
		.amdhsa_next_free_vgpr 254
		.amdhsa_next_free_sgpr 96
		.amdhsa_accum_offset 256
		.amdhsa_reserve_vcc 1
		.amdhsa_float_round_mode_32 0
		.amdhsa_float_round_mode_16_64 0
		.amdhsa_float_denorm_mode_32 3
		.amdhsa_float_denorm_mode_16_64 3
		.amdhsa_dx10_clamp 1
		.amdhsa_ieee_mode 1
		.amdhsa_fp16_overflow 0
		.amdhsa_tg_split 0
		.amdhsa_exception_fp_ieee_invalid_op 0
		.amdhsa_exception_fp_denorm_src 0
		.amdhsa_exception_fp_ieee_div_zero 0
		.amdhsa_exception_fp_ieee_overflow 0
		.amdhsa_exception_fp_ieee_underflow 0
		.amdhsa_exception_fp_ieee_inexact 0
		.amdhsa_exception_int_div_zero 0
	.end_amdhsa_kernel

; __global__ __launch_bounds__(NTHREADS, 2) void hymba_mega(Params p) {
amdhsa.kernels:
  - .agpr_count:     0
    .args:
      - .offset:         0
        .size:           136
        .value_kind:     by_value
      - .offset:         136
        .size:           4
        .value_kind:     hidden_block_count_x
      - .offset:         140
        .size:           4
        .value_kind:     hidden_block_count_y
      - .offset:         144
        .size:           4
        .value_kind:     hidden_block_count_z
      - .offset:         148
        .size:           2
        .value_kind:     hidden_group_size_x
      - .offset:         150
        .size:           2
        .value_kind:     hidden_group_size_y
      - .offset:         152
        .size:           2
        .value_kind:     hidden_group_size_z
      - .offset:         154
        .size:           2
        .value_kind:     hidden_remainder_x
      - .offset:         156
        .size:           2
        .value_kind:     hidden_remainder_y
      - .offset:         158
        .size:           2
        .value_kind:     hidden_remainder_z
      - .offset:         176
        .size:           8
        .value_kind:     hidden_global_offset_x
      - .offset:         184
        .size:           8
        .value_kind:     hidden_global_offset_y
      - .offset:         192
        .size:           8
        .value_kind:     hidden_global_offset_z
      - .offset:         200
        .size:           2
        .value_kind:     hidden_grid_dims
      - .offset:         224
        .size:           8
        .value_kind:     hidden_multigrid_sync_arg
      - .offset:         256
        .size:           4
        .value_kind:     hidden_dynamic_lds_size
    .group_segment_fixed_size: 0
    .kernarg_segment_align: 8
    .kernarg_segment_size: 392
    .language:       OpenCL C
    .language_version:
      - 2
      - 0
    .max_flat_workgroup_size: 512
    .name:           _Z10hymba_mega6Params
    .private_segment_fixed_size: 0
    .sgpr_count:     102
    .sgpr_spill_count: 0
    .symbol:         _Z10hymba_mega6Params.kd
    .uniform_work_group_size: 1
    .uses_dynamic_stack: false
    .vgpr_count:     254
    .vgpr_spill_count: 0
    .wavefront_size: 64
